# LayerNorm 4 (final, f32 out): row sums as DPP reductions like LN1-3
# baseline (speedup 1.0000x reference)
; __device__ __forceinline__ void ln_phase(int wv, h16* X, const float* g, const float* b, float* out32, int G, const float* part, float alpha, float beta) {
;     ...
; #pragma unroll
;         for (int e = 0; e < 32; ++e) s += v[e];
;         const float mean = wave_sum(s) * (1.f / DM); float s2 = 0.f;
; #pragma unroll
;         for (int e = 0; e < 32; ++e) { v[e] -= mean; s2 += v[e] * v[e]; }
;         const float rstd = 1.f / sqrtf(wave_sum(s2) * (1.f / DM) + LN_EPS);
; #pragma unroll
;         for (int j = 0; j < 4; ++j) { const int c0 = j * 512 + lane * 8;
;             const f32x4 g0 = *(const f32x4*)(g + c0), g1 = *(const f32x4*)(g + c0 + 4), b0 = *(const f32x4*)(b + c0), b1 = *(const f32x4*)(b + c0 + 4);
;             f32x4 o0, o1;
; #pragma unroll
;             for (int e = 0; e < 4; ++e) { o0[e] = v[j * 8 + e] * rstd * g0[e] + b0[e]; o1[e] = v[j * 8 + 4 + e] * rstd * g1[e] + b1[e]; }
;             if (out32) { *(f32x4*)(out32 + (size_t)row * DM + c0) = o0; *(f32x4*)(out32 + (size_t)row * DM + c0 + 4) = o1; }
.LBB0_2752:
	s_or_b64 exec, exec, s[2:3]
	v_add_f32_e32 v18, 0, v68
	v_add_f32_e32 v18, v69, v18
	v_add_f32_e32 v18, v66, v18
	v_add_f32_e32 v18, v67, v18
	v_add_f32_e32 v18, v64, v18
	v_add_f32_e32 v18, v65, v18
	v_add_f32_e32 v18, v28, v18
	v_add_f32_e32 v18, v29, v18
	v_add_f32_e32 v18, v30, v18
	v_add_f32_e32 v18, v31, v18
	v_add_f32_e32 v18, v70, v18
	v_add_f32_e32 v18, v71, v18
	v_add_f32_e32 v18, v24, v18
	v_add_f32_e32 v18, v25, v18
	v_add_f32_e32 v18, v72, v18
	v_add_f32_e32 v18, v73, v18
	v_add_f32_e32 v18, v26, v18
	v_add_f32_e32 v18, v27, v18
	v_add_f32_e32 v18, v74, v18
	v_add_f32_e32 v18, v75, v18
	v_add_f32_e32 v18, v20, v18
	v_add_f32_e32 v18, v21, v18
	v_add_f32_e32 v18, v76, v18
	v_add_f32_e32 v18, v77, v18
	v_add_f32_e32 v18, v22, v18
	v_add_f32_e32 v18, v23, v18
	v_add_f32_e32 v18, v78, v18
	v_add_f32_e32 v18, v79, v18
	v_add_f32_e32 v18, v16, v18
	v_add_f32_e32 v18, v17, v18
	v_add_f32_e32 v18, v80, v18
	v_add_f32_e32 v18, v81, v18
	v_mov_b32_e32 v160, v18
	s_nop 1
	v_add_f32_dpp v160, v160, v160 row_shr:1 row_mask:0xf bank_mask:0xf
	s_nop 1
	v_add_f32_dpp v160, v160, v160 row_shr:2 row_mask:0xf bank_mask:0xf
	s_nop 1
	v_add_f32_dpp v160, v160, v160 row_shr:4 row_mask:0xf bank_mask:0xf
	s_nop 1
	v_add_f32_dpp v160, v160, v160 row_shr:8 row_mask:0xf bank_mask:0xf
	s_nop 1
	v_add_f32_dpp v160, v160, v160 row_bcast:15 row_mask:0xa bank_mask:0xf
	s_nop 1
	v_add_f32_dpp v160, v160, v160 row_bcast:31 row_mask:0xc bank_mask:0xf
	s_nop 0
	v_readlane_b32 s98, v160, 63
	s_nop 1
	v_mov_b32_e32 v161, s98
	global_load_dwordx4 v[98:101], v[54:55], off offset:16
	global_load_dwordx4 v[102:105], v[54:55], off
	v_mov_b32_e32 v18, v161
	v_mul_f32_e32 v32, 0x3a000000, v18
	v_pk_add_f32 v[68:69], v[68:69], v[32:33] op_sel_hi:[1,0] neg_lo:[0,1] neg_hi:[0,1]
	v_pk_add_f32 v[66:67], v[66:67], v[32:33] op_sel_hi:[1,0] neg_lo:[0,1] neg_hi:[0,1]
	v_pk_mul_f32 v[124:125], v[68:69], v[68:69]
	v_pk_add_f32 v[88:89], v[30:31], v[32:33] op_sel_hi:[1,0] neg_lo:[0,1] neg_hi:[0,1]
	v_pk_add_f32 v[86:87], v[70:71], v[32:33] op_sel_hi:[1,0] neg_lo:[0,1] neg_hi:[0,1]
	v_pk_add_f32 v[92:93], v[24:25], v[32:33] op_sel_hi:[1,0] neg_lo:[0,1] neg_hi:[0,1]
	v_pk_add_f32 v[90:91], v[72:73], v[32:33] op_sel_hi:[1,0] neg_lo:[0,1] neg_hi:[0,1]
	v_pk_add_f32 v[82:83], v[26:27], v[32:33] op_sel_hi:[1,0] neg_lo:[0,1] neg_hi:[0,1]
	v_pk_add_f32 v[72:73], v[74:75], v[32:33] op_sel_hi:[1,0] neg_lo:[0,1] neg_hi:[0,1]
	v_pk_add_f32 v[84:85], v[20:21], v[32:33] op_sel_hi:[1,0] neg_lo:[0,1] neg_hi:[0,1]
	v_pk_add_f32 v[74:75], v[76:77], v[32:33] op_sel_hi:[1,0] neg_lo:[0,1] neg_hi:[0,1]
	v_pk_add_f32 v[30:31], v[22:23], v[32:33] op_sel_hi:[1,0] neg_lo:[0,1] neg_hi:[0,1]
	v_pk_add_f32 v[24:25], v[78:79], v[32:33] op_sel_hi:[1,0] neg_lo:[0,1] neg_hi:[0,1]
	v_pk_add_f32 v[70:71], v[16:17], v[32:33] op_sel_hi:[1,0] neg_lo:[0,1] neg_hi:[0,1]
	v_pk_add_f32 v[26:27], v[80:81], v[32:33] op_sel_hi:[1,0] neg_lo:[0,1] neg_hi:[0,1]
	v_pk_mul_f32 v[126:127], v[66:67], v[66:67]
	v_pk_add_f32 v[128:129], v[64:65], v[32:33] op_sel_hi:[1,0] neg_lo:[0,1] neg_hi:[0,1]
	v_pk_add_f32 v[28:29], v[28:29], v[32:33] op_sel_hi:[1,0] neg_lo:[0,1] neg_hi:[0,1]
	v_add_f32_e32 v32, v124, v125
	v_add_f32_e32 v32, v126, v32
	v_pk_mul_f32 v[64:65], v[128:129], v[128:129]
	v_add_f32_e32 v32, v127, v32
	v_add_f32_e32 v32, v64, v32
	v_pk_mul_f32 v[130:131], v[28:29], v[28:29]
	v_add_f32_e32 v32, v65, v32
	v_add_f32_e32 v32, v130, v32
	v_pk_mul_f32 v[76:77], v[88:89], v[88:89]
	v_add_f32_e32 v32, v131, v32
	v_add_f32_e32 v32, v76, v32
	v_pk_mul_f32 v[78:79], v[86:87], v[86:87]
	v_add_f32_e32 v32, v77, v32
	v_add_f32_e32 v32, v78, v32
	v_pk_mul_f32 v[80:81], v[92:93], v[92:93]
	v_add_f32_e32 v32, v79, v32
	v_add_f32_e32 v32, v80, v32
	v_pk_mul_f32 v[106:107], v[90:91], v[90:91]
	v_add_f32_e32 v32, v81, v32
	v_add_f32_e32 v32, v106, v32
	v_pk_mul_f32 v[108:109], v[82:83], v[82:83]
	v_add_f32_e32 v32, v107, v32
	v_add_f32_e32 v32, v108, v32
	v_pk_mul_f32 v[110:111], v[72:73], v[72:73]
	global_load_dwordx4 v[16:19], v[48:49], off offset:16
	global_load_dwordx4 v[20:23], v[48:49], off
	v_add_f32_e32 v32, v109, v32
	v_add_f32_e32 v32, v110, v32
	v_pk_mul_f32 v[112:113], v[84:85], v[84:85]
	v_add_f32_e32 v32, v111, v32
	v_add_f32_e32 v32, v112, v32
	v_pk_mul_f32 v[114:115], v[74:75], v[74:75]
	v_add_f32_e32 v32, v113, v32
	v_add_f32_e32 v32, v114, v32
	v_pk_mul_f32 v[116:117], v[30:31], v[30:31]
	v_add_f32_e32 v32, v115, v32
	v_add_f32_e32 v32, v116, v32
	v_pk_mul_f32 v[118:119], v[24:25], v[24:25]
	v_add_f32_e32 v32, v117, v32
	v_add_f32_e32 v32, v118, v32
	v_pk_mul_f32 v[120:121], v[70:71], v[70:71]
	v_add_f32_e32 v32, v119, v32
	v_add_f32_e32 v32, v120, v32
	v_pk_mul_f32 v[122:123], v[26:27], v[26:27]
	v_add_f32_e32 v32, v121, v32
	v_add_f32_e32 v32, v122, v32
	v_add_f32_e32 v32, v123, v32
	v_mov_b32_e32 v160, v32
	s_nop 1
	v_add_f32_dpp v160, v160, v160 row_shr:1 row_mask:0xf bank_mask:0xf
	s_nop 1
	v_add_f32_dpp v160, v160, v160 row_shr:2 row_mask:0xf bank_mask:0xf
	s_nop 1
	v_add_f32_dpp v160, v160, v160 row_shr:4 row_mask:0xf bank_mask:0xf
	s_nop 1
	v_add_f32_dpp v160, v160, v160 row_shr:8 row_mask:0xf bank_mask:0xf
	s_nop 1
	v_add_f32_dpp v160, v160, v160 row_bcast:15 row_mask:0xa bank_mask:0xf
	s_nop 1
	v_add_f32_dpp v160, v160, v160 row_bcast:31 row_mask:0xc bank_mask:0xf
	s_nop 0
	v_readlane_b32 s98, v160, 63
	s_nop 1
	v_mov_b32_e32 v161, s98
	v_cndmask_b32_e64 v65, 0, 1, s[4:5]
	v_mov_b32_e32 v32, v161
	v_fmamk_f32 v32, v32, 0x3a000000, v94
	v_mul_f32_e32 v64, 0x4f800000, v32
	v_cmp_gt_f32_e32 vcc, s35, v32
	s_nop 1
	v_cndmask_b32_e32 v32, v32, v64, vcc
	v_sqrt_f32_e32 v64, v32
	s_nop 0
	v_add_u32_e32 v76, -1, v64
	v_add_u32_e32 v77, 1, v64
	v_fma_f32 v78, -v76, v64, v32
	v_fma_f32 v79, -v77, v64, v32
	v_cmp_ge_f32_e64 s[2:3], 0, v78
	s_nop 1
	v_cndmask_b32_e64 v64, v64, v76, s[2:3]
	v_cmp_lt_f32_e64 s[2:3], 0, v79
	s_nop 1
	v_cndmask_b32_e64 v64, v64, v77, s[2:3]
	v_mul_f32_e32 v76, 0x37800000, v64
	v_cndmask_b32_e32 v64, v64, v76, vcc
	v_cmp_class_f32_e32 vcc, v32, v95
	s_nop 1
	v_cndmask_b32_e32 v32, v64, v32, vcc
	v_div_scale_f32 v64, s[2:3], v32, v32, 1.0
	v_rcp_f32_e32 v76, v64
	v_cmp_ne_u32_e64 s[2:3], 1, v65
	v_div_scale_f32 v65, vcc, 1.0, v32, 1.0
	v_fma_f32 v77, -v64, v76, 1.0
	v_fmac_f32_e32 v76, v77, v76
	v_mul_f32_e32 v77, v65, v76
	v_fma_f32 v78, -v64, v77, v65
	v_fmac_f32_e32 v77, v78, v76
	v_fma_f32 v64, -v64, v77, v65
	v_div_fmas_f32 v64, v64, v76, v77
	v_div_fixup_f32 v64, v64, v32, 1.0
	v_pk_mul_f32 v[68:69], v[68:69], v[64:65] op_sel_hi:[1,0]
	v_pk_mul_f32 v[76:77], v[128:129], v[64:65] op_sel_hi:[1,0]
	v_pk_mul_f32 v[66:67], v[66:67], v[64:65] op_sel_hi:[1,0]
	v_pk_mul_f32 v[28:29], v[28:29], v[64:65] op_sel_hi:[1,0]
	s_andn2_b64 vcc, exec, s[4:5]
	s_waitcnt vmcnt(0)
	v_pk_fma_f32 v[20:21], v[102:103], v[68:69], v[20:21]
	v_pk_fma_f32 v[16:17], v[98:99], v[76:77], v[16:17]
	v_pk_fma_f32 v[22:23], v[104:105], v[66:67], v[22:23]
	v_pk_fma_f32 v[18:19], v[100:101], v[28:29], v[18:19]
	s_cbranch_vccnz .LBB0_2763
; __device__ __forceinline__ void ln_phase(int wv, h16* X, const float* g, const float* b, float* out32, int G, const float* part, float alpha, float beta) {
;     ...
;             if (out32) { *(f32x4*)(out32 + (size_t)row * DM + c0) = o0; *(f32x4*)(out32 + (size_t)row * DM + c0 + 4) = o1; }
	global_store_dwordx4 v[42:43], v[20:23], off offset:-4096
	global_store_dwordx4 v[42:43], v[16:19], off offset:-4080
	v_lshl_add_u64 v[28:29], v[36:37], 0, v[34:35]
	s_cbranch_execnz .LBB0_2755
